# P5 layer1 tail round: 4-way split-K over 64 CUs with f32 slab exchange via unused y region
# speedup vs baseline: 1.0135x; 1.0135x over previous
;     __device__ __forceinline__ bool next(int i, Unit& u) const {
;         constexpr int NU = (33792 / BM) * NN;
;         const int L = i * G + ((NU - i * G < G) ? vp : v); if (L >= NU) return false;
;         constexpr int NM = 33792 / BM, NFULL = (NM / 8) * 8 * NN;
;         if (L < NFULL) { const int g = L / (8 * NN), idx = L % (8 * NN); u.pm = g * 8 + (idx & 7); u.pn = idx >> 3; }
;         else { constexpr int GS = NM % 8 ? NM % 8 : 8; const int idx = L - NFULL; u.pm = (NM / 8) * 8 + idx % GS; u.pn = idx / GS; }
;         return true;
;     }
; template <int KK, class Epi, class Sched, bool ALIGN_EPI = true>
; __device__ __forceinline__ void gemm_phase(LAS unsigned char* lds, const bf16* gA, const bf16* gBt, const Sched& S, const Epi& E, const int wid) {
;     ...
;         const bool has_next = S.next(ui + 1, nxt);
;         const char* nA = has_next ? (const char*)gA + (size_t)nxt.pm * tstep : cA; const char* nB = has_next ? (const char*)gBt + (size_t)nxt.pn * tstep : cB;
.LBB0_1284:
	s_add_i32 s42, s42, 1
	s_mul_i32 s6, s42, s64
	s_sub_i32 s7, 0x210, s6
	s_cmp_lt_i32 s7, s64
	s_cselect_b32 s16, s1, s0
	s_add_i32 s16, s16, s6
	s_cmp_lg_u32 s64, 0x100
	s_cbranch_scc1 .Lp5b_sch
	s_cmp_lg_u32 s42, 2
	s_cbranch_scc1 .Lp5b_sch
	s_movk_i32 s16, 0x210
	s_cmp_gt_u32 s86, 63
	s_cbranch_scc1 .Lp5b_sch
	s_and_b32 s7, s86, 7
	s_lshl_b32 s7, s7, 1
	s_bfe_u32 s16, s86, 0x10005
	s_add_i32 s16, s16, s7
	s_addk_i32 s16, 0x200
.Lp5b_sch:
	s_cmpk_lt_i32 s16, 0x210
	s_cselect_b64 s[14:15], -1, 0
	s_cmpk_gt_i32 s16, 0x20f
	s_cbranch_scc1 .LBB0_1289
	s_cmpk_gt_i32 s16, 0x1ff
	s_mov_b64 s[6:7], -1
	s_cbranch_scc0 .LBB0_1287
	s_add_i32 s6, s16, 0xfffffe00
	s_and_b32 s7, s16, 3
	s_or_b32 s54, s7, 0x80
	s_lshr_b32 s55, s6, 2
	s_mov_b64 s[6:7], 0

; template <int KK, class Epi, class Sched, bool ALIGN_EPI = true>
; __device__ __forceinline__ void gemm_phase(LAS unsigned char* lds, const bf16* gA, const bf16* gBt, const Sched& S, const Epi& E, const int wid) {
;     ...
;         const char* nA = has_next ? (const char*)gA + (size_t)nxt.pm * tstep : cA; const char* nB = has_next ? (const char*)gBt + (size_t)nxt.pn * tstep : cB;
; #pragma unroll 1
;         for (int t = 0; t < nt; t += 2) {
;             const bool last = (t == nt - 2);
;             const char* a1 = cA + (size_t)(t + 1) * kstep;
;             const char* a2 = last ? nA : cA + (size_t)(t + 2) * kstep; const char* b2 = last ? nB : cB + (size_t)(t + 2) * kstep;
;     ...
; #pragma unroll
;         for (int a = 0; a < 2; ++a)
; #pragma unroll
;             for (int b = 0; b < 2; ++b)
; #pragma unroll
;                 for (int m = 0; m < 4; ++m)
; #pragma unroll
;                     for (int n = 0; n < 2; ++n) acc[a][b][m][n] = (f32x4){0.f, 0.f, 0.f, 0.f};
;         cur = nxt; cA = nA; cB = nB; ++ui;
.LBB0_1293:
	s_cmp_lg_u32 s64, 0x100
	s_cbranch_scc1 .Lp5b_kof
	s_cmp_lg_u32 s42, 2
	s_cbranch_scc1 .Lp5b_kof
	s_cmp_gt_u32 s86, 63
	s_cbranch_scc1 .Lp5b_kof
	s_bfe_u32 s65, s86, 0x20003
	s_mul_i32 s66, s65, 0x600
	s_cmp_eq_u32 s65, 3
	s_cselect_b32 s65, 0x100, 0
	s_sub_i32 s66, s66, s65
	s_add_u32 s14, s14, s66
	s_addc_u32 s15, s15, 0
	s_add_u32 s16, s16, s66
	s_addc_u32 s17, s17, 0
.Lp5b_kof:
	s_add_u32 s59, s26, 0x100
	v_mov_b32_e32 v0, 0
	s_addc_u32 s60, s27, 0
	s_mov_b32 s61, -2
	s_cmp_lg_u32 s64, 0x100
	s_cbranch_scc1 .Lp5b_cnt
	s_cmp_lg_u32 s42, 3
	s_cbranch_scc1 .Lp5b_cnt
	s_bfe_u32 s65, s86, 0x10004
	s_lshl_b32 s65, s65, 1
	s_add_i32 s61, s65, 30
.Lp5b_cnt:
	v_mov_b32_e32 v1, v0
	v_mov_b32_e32 v2, v0
	v_mov_b32_e32 v3, v0
	v_mov_b32_e32 v4, v0
	v_mov_b32_e32 v5, v0
	v_mov_b32_e32 v6, v0
	v_mov_b32_e32 v7, v0
	v_mov_b32_e32 v12, v0
	v_mov_b32_e32 v13, v0
	v_mov_b32_e32 v14, v0
	v_mov_b32_e32 v15, v0
	v_mov_b32_e32 v20, v0
	v_mov_b32_e32 v21, v0
	v_mov_b32_e32 v22, v0
	v_mov_b32_e32 v23, v0
	v_mov_b32_e32 v28, v0
	v_mov_b32_e32 v29, v0
	v_mov_b32_e32 v30, v0
	v_mov_b32_e32 v31, v0
	v_mov_b32_e32 v36, v0
	v_mov_b32_e32 v37, v0
	v_mov_b32_e32 v38, v0
	v_mov_b32_e32 v39, v0
	v_mov_b32_e32 v44, v0
	v_mov_b32_e32 v45, v0
	v_mov_b32_e32 v46, v0
	v_mov_b32_e32 v47, v0
	v_mov_b32_e32 v52, v0
	v_mov_b32_e32 v53, v0
	v_mov_b32_e32 v54, v0
	v_mov_b32_e32 v55, v0
	v_mov_b32_e32 v8, v0
	v_mov_b32_e32 v9, v0
	v_mov_b32_e32 v10, v0
	v_mov_b32_e32 v11, v0
	v_mov_b32_e32 v16, v0
	v_mov_b32_e32 v17, v0
	v_mov_b32_e32 v18, v0
	v_mov_b32_e32 v19, v0
	v_mov_b32_e32 v24, v0
	v_mov_b32_e32 v25, v0
	v_mov_b32_e32 v26, v0
	v_mov_b32_e32 v27, v0
	v_mov_b32_e32 v32, v0
	v_mov_b32_e32 v33, v0
	v_mov_b32_e32 v34, v0
	v_mov_b32_e32 v35, v0
	v_mov_b32_e32 v40, v0
	v_mov_b32_e32 v41, v0
	v_mov_b32_e32 v42, v0
	v_mov_b32_e32 v43, v0
	v_mov_b32_e32 v48, v0
	v_mov_b32_e32 v49, v0
	v_mov_b32_e32 v50, v0
	v_mov_b32_e32 v51, v0
	v_mov_b32_e32 v56, v0
	v_mov_b32_e32 v57, v0
	v_mov_b32_e32 v58, v0
	v_mov_b32_e32 v59, v0
	v_mov_b32_e32 v60, v0
	v_mov_b32_e32 v61, v0
	v_mov_b32_e32 v62, v0
	v_mov_b32_e32 v63, v0
	v_mov_b32_e32 v64, v0
	v_mov_b32_e32 v65, v0
	v_mov_b32_e32 v66, v0
	v_mov_b32_e32 v67, v0
	v_mov_b32_e32 v68, v0
	v_mov_b32_e32 v69, v0
	v_mov_b32_e32 v70, v0
	v_mov_b32_e32 v71, v0
	v_mov_b32_e32 v76, v0
	v_mov_b32_e32 v77, v0
	v_mov_b32_e32 v78, v0
	v_mov_b32_e32 v79, v0
	v_mov_b32_e32 v84, v0
	v_mov_b32_e32 v85, v0
	v_mov_b32_e32 v86, v0
	v_mov_b32_e32 v87, v0
	v_mov_b32_e32 v92, v0
	v_mov_b32_e32 v93, v0
	v_mov_b32_e32 v94, v0
	v_mov_b32_e32 v95, v0
	v_mov_b32_e32 v100, v0
	v_mov_b32_e32 v101, v0
	v_mov_b32_e32 v102, v0
	v_mov_b32_e32 v103, v0
	v_mov_b32_e32 v108, v0
	v_mov_b32_e32 v109, v0
	v_mov_b32_e32 v110, v0
	v_mov_b32_e32 v111, v0
	v_mov_b32_e32 v116, v0
	v_mov_b32_e32 v117, v0
	v_mov_b32_e32 v118, v0
	v_mov_b32_e32 v119, v0
	v_mov_b32_e32 v72, v0
	v_mov_b32_e32 v73, v0
	v_mov_b32_e32 v74, v0
	v_mov_b32_e32 v75, v0
	v_mov_b32_e32 v80, v0
	v_mov_b32_e32 v81, v0
	v_mov_b32_e32 v82, v0
	v_mov_b32_e32 v83, v0
	v_mov_b32_e32 v88, v0
	v_mov_b32_e32 v89, v0
	v_mov_b32_e32 v90, v0
	v_mov_b32_e32 v91, v0
	v_mov_b32_e32 v96, v0
	v_mov_b32_e32 v97, v0
	v_mov_b32_e32 v98, v0
	v_mov_b32_e32 v99, v0
	v_mov_b32_e32 v104, v0
	v_mov_b32_e32 v105, v0
	v_mov_b32_e32 v106, v0
	v_mov_b32_e32 v107, v0
	v_mov_b32_e32 v112, v0
	v_mov_b32_e32 v113, v0
	v_mov_b32_e32 v114, v0
	v_mov_b32_e32 v115, v0
	v_mov_b32_e32 v120, v0
	v_mov_b32_e32 v121, v0
	v_mov_b32_e32 v122, v0
	v_mov_b32_e32 v123, v0
	v_mov_b32_e32 v124, v0
	v_mov_b32_e32 v125, v0
	v_mov_b32_e32 v126, v0
	v_mov_b32_e32 v127, v0

; #define PG8_BAR __builtin_amdgcn_s_barrier()
; #define EPI_ENTRY() GAS unsigned char* wsg_ = (GAS unsigned char*)ws_; GAS float* outg_ = (GAS float*)out_; asm volatile("" : "+s"(wsg_), "+s"(outg_)); unsigned char* ws = (unsigned char*)wsg_; float* out = (float*)outg_; const int lane_ = lane_id(); const int fr = lane_ & 15, fq = lane_ >> 4; (void)ws; (void)out
; template <int KK, class Epi, class Sched, bool ALIGN_EPI = true>
; __device__ __forceinline__ void gemm_phase(LAS unsigned char* lds, const bf16* gA, const bf16* gBt, const Sched& S, const Epi& E, const int wid) {
;     ...
;         if constexpr (ALIGN_EPI) { if (wr == 0) PG8_BAR; }
;         E(acc, cur, wr, wc, fr, fq);
;         if (!has_next) break;
;     __device__ __forceinline__ void operator()(AccRef acc, const pg8::Unit& u, int wr, int wc, int, int) const {
;         EPI_ENTRY();
;         bf16* HB = (bf16*)(ws + WS_HB); const bf16* RB = (const bf16*)(ws + (from_xb ? WS_XB : WS_HB)); float* ssq = (float*)(ws + WS_SSQ) + ssq_off;
; #pragma unroll
;         for (int ai = 0; ai < 2; ++ai) {
;             f32x4 r0[4][2], r1[4][2];
.LBB0_1297:
	s_cmp_lg_u32 s64, 0x100
	s_cbranch_scc1 .Lp5b_epi
	s_cmp_lg_u32 s42, 3
	s_cbranch_scc1 .Lp5b_epi
	s_bfe_u32 s65, s86, 0x20003
	s_and_b32 s66, s86, 7
	s_lshl_b32 s66, s66, 1
	s_bfe_u32 s67, s86, 0x10005
	s_add_i32 s66, s66, s67
	v_readlane_b32 s67, v249, 0
	v_lshlrev_b32_e32 v140, 4, v196
	s_nop 1
	s_lshl_b32 s68, s67, 10
	v_add_u32_e32 v140, s68, v140
	s_mul_i32 s68, s66, 3
	s_lshl_b32 s68, s68, 18
	s_add_u32 s70, s22, s68
	s_addc_u32 s71, s23, 0
	s_add_u32 s70, s70, 0x0
	s_addc_u32 s71, s71, 0
	s_cmp_eq_u32 s65, 0
	s_cbranch_scc1 .Lp5b_cons
	s_add_i32 s68, s65, -1
	s_lshl_b32 s68, s68, 18
	s_add_u32 s70, s70, s68
	s_addc_u32 s71, s71, 0
	s_nop 7
	global_store_dwordx4 v140, v[0:3], s[70:71] sc0 sc1
	s_add_u32 s70, s70, 0x2000
	s_addc_u32 s71, s71, 0
	global_store_dwordx4 v140, v[4:7], s[70:71] sc0 sc1
	s_add_u32 s70, s70, 0x2000
	s_addc_u32 s71, s71, 0
	global_store_dwordx4 v140, v[8:11], s[70:71] sc0 sc1
	s_add_u32 s70, s70, 0x2000
	s_addc_u32 s71, s71, 0
	global_store_dwordx4 v140, v[12:15], s[70:71] sc0 sc1
	s_add_u32 s70, s70, 0x2000
	s_addc_u32 s71, s71, 0
	global_store_dwordx4 v140, v[16:19], s[70:71] sc0 sc1
	s_add_u32 s70, s70, 0x2000
	s_addc_u32 s71, s71, 0
	global_store_dwordx4 v140, v[20:23], s[70:71] sc0 sc1
	s_add_u32 s70, s70, 0x2000
	s_addc_u32 s71, s71, 0
	global_store_dwordx4 v140, v[24:27], s[70:71] sc0 sc1
	s_add_u32 s70, s70, 0x2000
	s_addc_u32 s71, s71, 0
	global_store_dwordx4 v140, v[28:31], s[70:71] sc0 sc1
	s_add_u32 s70, s70, 0x2000
	s_addc_u32 s71, s71, 0
	global_store_dwordx4 v140, v[32:35], s[70:71] sc0 sc1
	s_add_u32 s70, s70, 0x2000
	s_addc_u32 s71, s71, 0
	global_store_dwordx4 v140, v[36:39], s[70:71] sc0 sc1
	s_add_u32 s70, s70, 0x2000
	s_addc_u32 s71, s71, 0
	global_store_dwordx4 v140, v[40:43], s[70:71] sc0 sc1
	s_add_u32 s70, s70, 0x2000
	s_addc_u32 s71, s71, 0
	global_store_dwordx4 v140, v[44:47], s[70:71] sc0 sc1
	s_add_u32 s70, s70, 0x2000
	s_addc_u32 s71, s71, 0
	global_store_dwordx4 v140, v[48:51], s[70:71] sc0 sc1
	s_add_u32 s70, s70, 0x2000
	s_addc_u32 s71, s71, 0
	global_store_dwordx4 v140, v[52:55], s[70:71] sc0 sc1
	s_add_u32 s70, s70, 0x2000
	s_addc_u32 s71, s71, 0
	global_store_dwordx4 v140, v[56:59], s[70:71] sc0 sc1
	s_add_u32 s70, s70, 0x2000
	s_addc_u32 s71, s71, 0
	global_store_dwordx4 v140, v[60:63], s[70:71] sc0 sc1
	s_add_u32 s70, s70, 0x2000
	s_addc_u32 s71, s71, 0
	global_store_dwordx4 v140, v[64:67], s[70:71] sc0 sc1
	s_add_u32 s70, s70, 0x2000
	s_addc_u32 s71, s71, 0
	global_store_dwordx4 v140, v[68:71], s[70:71] sc0 sc1
	s_add_u32 s70, s70, 0x2000
	s_addc_u32 s71, s71, 0
	global_store_dwordx4 v140, v[72:75], s[70:71] sc0 sc1
	s_add_u32 s70, s70, 0x2000
	s_addc_u32 s71, s71, 0
	global_store_dwordx4 v140, v[76:79], s[70:71] sc0 sc1
	s_add_u32 s70, s70, 0x2000
	s_addc_u32 s71, s71, 0
	global_store_dwordx4 v140, v[80:83], s[70:71] sc0 sc1
	s_add_u32 s70, s70, 0x2000
	s_addc_u32 s71, s71, 0
	global_store_dwordx4 v140, v[84:87], s[70:71] sc0 sc1
	s_add_u32 s70, s70, 0x2000
	s_addc_u32 s71, s71, 0
	global_store_dwordx4 v140, v[88:91], s[70:71] sc0 sc1
	s_add_u32 s70, s70, 0x2000
	s_addc_u32 s71, s71, 0
	global_store_dwordx4 v140, v[92:95], s[70:71] sc0 sc1
	s_add_u32 s70, s70, 0x2000
	s_addc_u32 s71, s71, 0
	global_store_dwordx4 v140, v[96:99], s[70:71] sc0 sc1
	s_add_u32 s70, s70, 0x2000
	s_addc_u32 s71, s71, 0
	global_store_dwordx4 v140, v[100:103], s[70:71] sc0 sc1
	s_add_u32 s70, s70, 0x2000
	s_addc_u32 s71, s71, 0
	global_store_dwordx4 v140, v[104:107], s[70:71] sc0 sc1
	s_add_u32 s70, s70, 0x2000
	s_addc_u32 s71, s71, 0
	global_store_dwordx4 v140, v[108:111], s[70:71] sc0 sc1
	s_add_u32 s70, s70, 0x2000
	s_addc_u32 s71, s71, 0
	global_store_dwordx4 v140, v[112:115], s[70:71] sc0 sc1
	s_add_u32 s70, s70, 0x2000
	s_addc_u32 s71, s71, 0
	global_store_dwordx4 v140, v[116:119], s[70:71] sc0 sc1
	s_add_u32 s70, s70, 0x2000
	s_addc_u32 s71, s71, 0
	global_store_dwordx4 v140, v[120:123], s[70:71] sc0 sc1
	s_add_u32 s70, s70, 0x2000
	s_addc_u32 s71, s71, 0
	global_store_dwordx4 v140, v[124:127], s[70:71] sc0 sc1
	s_waitcnt vmcnt(0)
	s_lshl_b32 s68, s66, 2
	s_add_i32 s68, s68, s65
	s_lshl_b32 s68, s68, 2
	v_mov_b32_e32 v141, s68
	v_mov_b32_e32 v142, 1
	s_mov_b64 s[72:73], exec
	s_mov_b64 exec, 1
	global_atomic_add v141, v142, s[20:21] offset:3200
	s_mov_b64 exec, s[72:73]
	s_branch .LBB0_1300
.Lp5b_cons:
	s_lshl_b32 s68, s66, 4
	v_mov_b32_e32 v141, s68
.Lp5b_poll2:
	global_load_dword v142, v141, s[20:21] offset:3208 sc1
	s_waitcnt vmcnt(0)
	v_readfirstlane_b32 s69, v142
	s_nop 0
	s_cmp_ge_u32 s69, 8
	s_cbranch_scc1 .Lp5b_go2
	s_sleep 1
	s_branch .Lp5b_poll2
; #define PG8_BAR __builtin_amdgcn_s_barrier()
; template <int KK, class Epi, class Sched, bool ALIGN_EPI = true>
; __device__ __forceinline__ void gemm_phase(LAS unsigned char* lds, const bf16* gA, const bf16* gBt, const Sched& S, const Epi& E, const int wid) {
;     ...
;         if constexpr (ALIGN_EPI) { if (wr == 0) PG8_BAR; }
;         E(acc, cur, wr, wc, fr, fq);
.Lp5b_go2:
	s_add_u32 s72, s70, 0x40000
	s_addc_u32 s73, s71, 0
	global_load_dwordx4 v[200:203], v140, s[72:73] sc0 sc1
	s_add_u32 s72, s72, 0x2000
	s_addc_u32 s73, s73, 0
	global_load_dwordx4 v[204:207], v140, s[72:73] sc0 sc1
	s_add_u32 s72, s72, 0x2000
	s_addc_u32 s73, s73, 0
	global_load_dwordx4 v[208:211], v140, s[72:73] sc0 sc1
	s_add_u32 s72, s72, 0x2000
	s_addc_u32 s73, s73, 0
	global_load_dwordx4 v[212:215], v140, s[72:73] sc0 sc1
	s_add_u32 s72, s72, 0x2000
	s_addc_u32 s73, s73, 0
	global_load_dwordx4 v[216:219], v140, s[72:73] sc0 sc1
	s_add_u32 s72, s72, 0x2000
	s_addc_u32 s73, s73, 0
	global_load_dwordx4 v[220:223], v140, s[72:73] sc0 sc1
	s_add_u32 s72, s72, 0x2000
	s_addc_u32 s73, s73, 0
	global_load_dwordx4 v[224:227], v140, s[72:73] sc0 sc1
	s_add_u32 s72, s72, 0x2000
	s_addc_u32 s73, s73, 0
	global_load_dwordx4 v[228:231], v140, s[72:73] sc0 sc1
	s_add_u32 s72, s72, 0x2000
	s_addc_u32 s73, s73, 0
	global_load_dwordx4 v[232:235], v140, s[72:73] sc0 sc1
	s_add_u32 s72, s72, 0x2000
	s_addc_u32 s73, s73, 0
	global_load_dwordx4 v[236:239], v140, s[72:73] sc0 sc1
	s_add_u32 s72, s72, 0x2000
	s_addc_u32 s73, s73, 0
	global_load_dwordx4 v[240:243], v140, s[72:73] sc0 sc1
	s_add_u32 s72, s72, 0x2000
	s_addc_u32 s73, s73, 0
	global_load_dwordx4 v[244:247], v140, s[72:73] sc0 sc1
	s_add_u32 s72, s72, 0x2000
	s_addc_u32 s73, s73, 0
	global_load_dwordx4 v[160:163], v140, s[72:73] sc0 sc1
	s_add_u32 s72, s72, 0x2000
	s_addc_u32 s73, s73, 0
	global_load_dwordx4 v[164:167], v140, s[72:73] sc0 sc1
	s_add_u32 s72, s72, 0x2000
	s_addc_u32 s73, s73, 0
	global_load_dwordx4 v[168:171], v140, s[72:73] sc0 sc1
	s_add_u32 s72, s72, 0x2000
	s_addc_u32 s73, s73, 0
	global_load_dwordx4 v[172:175], v140, s[72:73] sc0 sc1
	s_add_u32 s72, s72, 0x2000
	s_addc_u32 s73, s73, 0
	s_waitcnt vmcnt(15)
	v_pk_add_f32 v[0:1], v[0:1], v[200:201]
	v_pk_add_f32 v[2:3], v[2:3], v[202:203]
	s_waitcnt vmcnt(14)
	v_pk_add_f32 v[4:5], v[4:5], v[204:205]
	v_pk_add_f32 v[6:7], v[6:7], v[206:207]
	s_waitcnt vmcnt(13)
	v_pk_add_f32 v[8:9], v[8:9], v[208:209]
	v_pk_add_f32 v[10:11], v[10:11], v[210:211]
	s_waitcnt vmcnt(12)
	v_pk_add_f32 v[12:13], v[12:13], v[212:213]
	v_pk_add_f32 v[14:15], v[14:15], v[214:215]
	s_waitcnt vmcnt(11)
	v_pk_add_f32 v[16:17], v[16:17], v[216:217]
	v_pk_add_f32 v[18:19], v[18:19], v[218:219]
	s_waitcnt vmcnt(10)
	v_pk_add_f32 v[20:21], v[20:21], v[220:221]
	v_pk_add_f32 v[22:23], v[22:23], v[222:223]
	s_waitcnt vmcnt(9)
	v_pk_add_f32 v[24:25], v[24:25], v[224:225]
	v_pk_add_f32 v[26:27], v[26:27], v[226:227]
	s_waitcnt vmcnt(8)
	v_pk_add_f32 v[28:29], v[28:29], v[228:229]
	v_pk_add_f32 v[30:31], v[30:31], v[230:231]
	s_waitcnt vmcnt(7)
	v_pk_add_f32 v[32:33], v[32:33], v[232:233]
	v_pk_add_f32 v[34:35], v[34:35], v[234:235]
	s_waitcnt vmcnt(6)
	v_pk_add_f32 v[36:37], v[36:37], v[236:237]
	v_pk_add_f32 v[38:39], v[38:39], v[238:239]
	s_waitcnt vmcnt(5)
	v_pk_add_f32 v[40:41], v[40:41], v[240:241]
	v_pk_add_f32 v[42:43], v[42:43], v[242:243]
	s_waitcnt vmcnt(4)
	v_pk_add_f32 v[44:45], v[44:45], v[244:245]
	v_pk_add_f32 v[46:47], v[46:47], v[246:247]
	s_waitcnt vmcnt(3)
	v_pk_add_f32 v[48:49], v[48:49], v[160:161]
	v_pk_add_f32 v[50:51], v[50:51], v[162:163]
	s_waitcnt vmcnt(2)
	v_pk_add_f32 v[52:53], v[52:53], v[164:165]
	v_pk_add_f32 v[54:55], v[54:55], v[166:167]
	s_waitcnt vmcnt(1)
	v_pk_add_f32 v[56:57], v[56:57], v[168:169]
	v_pk_add_f32 v[58:59], v[58:59], v[170:171]
	s_waitcnt vmcnt(0)
	v_pk_add_f32 v[60:61], v[60:61], v[172:173]
	v_pk_add_f32 v[62:63], v[62:63], v[174:175]
	global_load_dwordx4 v[200:203], v140, s[72:73] sc0 sc1
	s_add_u32 s72, s72, 0x2000
	s_addc_u32 s73, s73, 0
	global_load_dwordx4 v[204:207], v140, s[72:73] sc0 sc1
	s_add_u32 s72, s72, 0x2000
	s_addc_u32 s73, s73, 0
	global_load_dwordx4 v[208:211], v140, s[72:73] sc0 sc1
	s_add_u32 s72, s72, 0x2000
	s_addc_u32 s73, s73, 0
	global_load_dwordx4 v[212:215], v140, s[72:73] sc0 sc1
	s_add_u32 s72, s72, 0x2000
	s_addc_u32 s73, s73, 0
	global_load_dwordx4 v[216:219], v140, s[72:73] sc0 sc1
	s_add_u32 s72, s72, 0x2000
	s_addc_u32 s73, s73, 0
	global_load_dwordx4 v[220:223], v140, s[72:73] sc0 sc1
	s_add_u32 s72, s72, 0x2000
	s_addc_u32 s73, s73, 0
	global_load_dwordx4 v[224:227], v140, s[72:73] sc0 sc1
	s_add_u32 s72, s72, 0x2000
	s_addc_u32 s73, s73, 0
	global_load_dwordx4 v[228:231], v140, s[72:73] sc0 sc1
	s_add_u32 s72, s72, 0x2000
	s_addc_u32 s73, s73, 0
	global_load_dwordx4 v[232:235], v140, s[72:73] sc0 sc1
	s_add_u32 s72, s72, 0x2000
	s_addc_u32 s73, s73, 0
	global_load_dwordx4 v[236:239], v140, s[72:73] sc0 sc1
	s_add_u32 s72, s72, 0x2000
	s_addc_u32 s73, s73, 0
	global_load_dwordx4 v[240:243], v140, s[72:73] sc0 sc1
	s_add_u32 s72, s72, 0x2000
	s_addc_u32 s73, s73, 0
	global_load_dwordx4 v[244:247], v140, s[72:73] sc0 sc1
	s_add_u32 s72, s72, 0x2000
	s_addc_u32 s73, s73, 0
	global_load_dwordx4 v[160:163], v140, s[72:73] sc0 sc1
	s_add_u32 s72, s72, 0x2000
	s_addc_u32 s73, s73, 0
	global_load_dwordx4 v[164:167], v140, s[72:73] sc0 sc1
	s_add_u32 s72, s72, 0x2000
	s_addc_u32 s73, s73, 0
	global_load_dwordx4 v[168:171], v140, s[72:73] sc0 sc1
	s_add_u32 s72, s72, 0x2000
	s_addc_u32 s73, s73, 0
	global_load_dwordx4 v[172:175], v140, s[72:73] sc0 sc1
	s_add_u32 s72, s72, 0x2000
	s_addc_u32 s73, s73, 0
	s_waitcnt vmcnt(15)
	v_pk_add_f32 v[64:65], v[64:65], v[200:201]
	v_pk_add_f32 v[66:67], v[66:67], v[202:203]
	s_waitcnt vmcnt(14)
	v_pk_add_f32 v[68:69], v[68:69], v[204:205]
	v_pk_add_f32 v[70:71], v[70:71], v[206:207]
	s_waitcnt vmcnt(13)
	v_pk_add_f32 v[72:73], v[72:73], v[208:209]
	v_pk_add_f32 v[74:75], v[74:75], v[210:211]
	s_waitcnt vmcnt(12)
; #define PG8_BAR __builtin_amdgcn_s_barrier()
; template <int KK, class Epi, class Sched, bool ALIGN_EPI = true>
; __device__ __forceinline__ void gemm_phase(LAS unsigned char* lds, const bf16* gA, const bf16* gBt, const Sched& S, const Epi& E, const int wid) {
;     ...
;         if constexpr (ALIGN_EPI) { if (wr == 0) PG8_BAR; }
;         E(acc, cur, wr, wc, fr, fq);
	v_pk_add_f32 v[76:77], v[76:77], v[212:213]
	v_pk_add_f32 v[78:79], v[78:79], v[214:215]
	s_waitcnt vmcnt(11)
	v_pk_add_f32 v[80:81], v[80:81], v[216:217]
	v_pk_add_f32 v[82:83], v[82:83], v[218:219]
	s_waitcnt vmcnt(10)
	v_pk_add_f32 v[84:85], v[84:85], v[220:221]
	v_pk_add_f32 v[86:87], v[86:87], v[222:223]
	s_waitcnt vmcnt(9)
	v_pk_add_f32 v[88:89], v[88:89], v[224:225]
	v_pk_add_f32 v[90:91], v[90:91], v[226:227]
	s_waitcnt vmcnt(8)
	v_pk_add_f32 v[92:93], v[92:93], v[228:229]
	v_pk_add_f32 v[94:95], v[94:95], v[230:231]
	s_waitcnt vmcnt(7)
	v_pk_add_f32 v[96:97], v[96:97], v[232:233]
	v_pk_add_f32 v[98:99], v[98:99], v[234:235]
	s_waitcnt vmcnt(6)
	v_pk_add_f32 v[100:101], v[100:101], v[236:237]
	v_pk_add_f32 v[102:103], v[102:103], v[238:239]
	s_waitcnt vmcnt(5)
	v_pk_add_f32 v[104:105], v[104:105], v[240:241]
	v_pk_add_f32 v[106:107], v[106:107], v[242:243]
	s_waitcnt vmcnt(4)
	v_pk_add_f32 v[108:109], v[108:109], v[244:245]
	v_pk_add_f32 v[110:111], v[110:111], v[246:247]
	s_waitcnt vmcnt(3)
	v_pk_add_f32 v[112:113], v[112:113], v[160:161]
	v_pk_add_f32 v[114:115], v[114:115], v[162:163]
	s_waitcnt vmcnt(2)
	v_pk_add_f32 v[116:117], v[116:117], v[164:165]
	v_pk_add_f32 v[118:119], v[118:119], v[166:167]
	s_waitcnt vmcnt(1)
	v_pk_add_f32 v[120:121], v[120:121], v[168:169]
	v_pk_add_f32 v[122:123], v[122:123], v[170:171]
	s_waitcnt vmcnt(0)
	v_pk_add_f32 v[124:125], v[124:125], v[172:173]
	v_pk_add_f32 v[126:127], v[126:127], v[174:175]
.Lp5b_poll3:
	global_load_dword v142, v141, s[20:21] offset:3212 sc1
	s_waitcnt vmcnt(0)
	v_readfirstlane_b32 s69, v142
	s_nop 0
	s_cmp_ge_u32 s69, 8
	s_cbranch_scc1 .Lp5b_go3
	s_sleep 1
	s_branch .Lp5b_poll3
.Lp5b_go3:
	s_add_u32 s72, s70, 0x80000
	s_addc_u32 s73, s71, 0
	global_load_dwordx4 v[200:203], v140, s[72:73] sc0 sc1
	s_add_u32 s72, s72, 0x2000
	s_addc_u32 s73, s73, 0
	global_load_dwordx4 v[204:207], v140, s[72:73] sc0 sc1
	s_add_u32 s72, s72, 0x2000
	s_addc_u32 s73, s73, 0
	global_load_dwordx4 v[208:211], v140, s[72:73] sc0 sc1
	s_add_u32 s72, s72, 0x2000
	s_addc_u32 s73, s73, 0
	global_load_dwordx4 v[212:215], v140, s[72:73] sc0 sc1
	s_add_u32 s72, s72, 0x2000
	s_addc_u32 s73, s73, 0
	global_load_dwordx4 v[216:219], v140, s[72:73] sc0 sc1
	s_add_u32 s72, s72, 0x2000
	s_addc_u32 s73, s73, 0
	global_load_dwordx4 v[220:223], v140, s[72:73] sc0 sc1
	s_add_u32 s72, s72, 0x2000
	s_addc_u32 s73, s73, 0
	global_load_dwordx4 v[224:227], v140, s[72:73] sc0 sc1
	s_add_u32 s72, s72, 0x2000
	s_addc_u32 s73, s73, 0
	global_load_dwordx4 v[228:231], v140, s[72:73] sc0 sc1
	s_add_u32 s72, s72, 0x2000
	s_addc_u32 s73, s73, 0
	global_load_dwordx4 v[232:235], v140, s[72:73] sc0 sc1
	s_add_u32 s72, s72, 0x2000
	s_addc_u32 s73, s73, 0
	global_load_dwordx4 v[236:239], v140, s[72:73] sc0 sc1
	s_add_u32 s72, s72, 0x2000
	s_addc_u32 s73, s73, 0
	global_load_dwordx4 v[240:243], v140, s[72:73] sc0 sc1
	s_add_u32 s72, s72, 0x2000
	s_addc_u32 s73, s73, 0
	global_load_dwordx4 v[244:247], v140, s[72:73] sc0 sc1
	s_add_u32 s72, s72, 0x2000
	s_addc_u32 s73, s73, 0
	global_load_dwordx4 v[160:163], v140, s[72:73] sc0 sc1
	s_add_u32 s72, s72, 0x2000
	s_addc_u32 s73, s73, 0
	global_load_dwordx4 v[164:167], v140, s[72:73] sc0 sc1
	s_add_u32 s72, s72, 0x2000
	s_addc_u32 s73, s73, 0
	global_load_dwordx4 v[168:171], v140, s[72:73] sc0 sc1
	s_add_u32 s72, s72, 0x2000
	s_addc_u32 s73, s73, 0
	global_load_dwordx4 v[172:175], v140, s[72:73] sc0 sc1
	s_add_u32 s72, s72, 0x2000
	s_addc_u32 s73, s73, 0
	s_waitcnt vmcnt(15)
	v_pk_add_f32 v[0:1], v[0:1], v[200:201]
	v_pk_add_f32 v[2:3], v[2:3], v[202:203]
	s_waitcnt vmcnt(14)
	v_pk_add_f32 v[4:5], v[4:5], v[204:205]
	v_pk_add_f32 v[6:7], v[6:7], v[206:207]
	s_waitcnt vmcnt(13)
	v_pk_add_f32 v[8:9], v[8:9], v[208:209]
	v_pk_add_f32 v[10:11], v[10:11], v[210:211]
	s_waitcnt vmcnt(12)
	v_pk_add_f32 v[12:13], v[12:13], v[212:213]
	v_pk_add_f32 v[14:15], v[14:15], v[214:215]
	s_waitcnt vmcnt(11)
	v_pk_add_f32 v[16:17], v[16:17], v[216:217]
	v_pk_add_f32 v[18:19], v[18:19], v[218:219]
	s_waitcnt vmcnt(10)
	v_pk_add_f32 v[20:21], v[20:21], v[220:221]
	v_pk_add_f32 v[22:23], v[22:23], v[222:223]
	s_waitcnt vmcnt(9)
	v_pk_add_f32 v[24:25], v[24:25], v[224:225]
	v_pk_add_f32 v[26:27], v[26:27], v[226:227]
	s_waitcnt vmcnt(8)
	v_pk_add_f32 v[28:29], v[28:29], v[228:229]
	v_pk_add_f32 v[30:31], v[30:31], v[230:231]
	s_waitcnt vmcnt(7)
	v_pk_add_f32 v[32:33], v[32:33], v[232:233]
	v_pk_add_f32 v[34:35], v[34:35], v[234:235]
	s_waitcnt vmcnt(6)
	v_pk_add_f32 v[36:37], v[36:37], v[236:237]
	v_pk_add_f32 v[38:39], v[38:39], v[238:239]
	s_waitcnt vmcnt(5)
	v_pk_add_f32 v[40:41], v[40:41], v[240:241]
	v_pk_add_f32 v[42:43], v[42:43], v[242:243]
	s_waitcnt vmcnt(4)
	v_pk_add_f32 v[44:45], v[44:45], v[244:245]
	v_pk_add_f32 v[46:47], v[46:47], v[246:247]
	s_waitcnt vmcnt(3)
	v_pk_add_f32 v[48:49], v[48:49], v[160:161]
	v_pk_add_f32 v[50:51], v[50:51], v[162:163]
	s_waitcnt vmcnt(2)
	v_pk_add_f32 v[52:53], v[52:53], v[164:165]
	v_pk_add_f32 v[54:55], v[54:55], v[166:167]
	s_waitcnt vmcnt(1)
	v_pk_add_f32 v[56:57], v[56:57], v[168:169]
	v_pk_add_f32 v[58:59], v[58:59], v[170:171]
	s_waitcnt vmcnt(0)
; #define PG8_BAR __builtin_amdgcn_s_barrier()
; template <int KK, class Epi, class Sched, bool ALIGN_EPI = true>
; __device__ __forceinline__ void gemm_phase(LAS unsigned char* lds, const bf16* gA, const bf16* gBt, const Sched& S, const Epi& E, const int wid) {
;     ...
;         if constexpr (ALIGN_EPI) { if (wr == 0) PG8_BAR; }
;         E(acc, cur, wr, wc, fr, fq);
	v_pk_add_f32 v[60:61], v[60:61], v[172:173]
	v_pk_add_f32 v[62:63], v[62:63], v[174:175]
	global_load_dwordx4 v[200:203], v140, s[72:73] sc0 sc1
	s_add_u32 s72, s72, 0x2000
	s_addc_u32 s73, s73, 0
	global_load_dwordx4 v[204:207], v140, s[72:73] sc0 sc1
	s_add_u32 s72, s72, 0x2000
	s_addc_u32 s73, s73, 0
	global_load_dwordx4 v[208:211], v140, s[72:73] sc0 sc1
	s_add_u32 s72, s72, 0x2000
	s_addc_u32 s73, s73, 0
	global_load_dwordx4 v[212:215], v140, s[72:73] sc0 sc1
	s_add_u32 s72, s72, 0x2000
	s_addc_u32 s73, s73, 0
	global_load_dwordx4 v[216:219], v140, s[72:73] sc0 sc1
	s_add_u32 s72, s72, 0x2000
	s_addc_u32 s73, s73, 0
	global_load_dwordx4 v[220:223], v140, s[72:73] sc0 sc1
	s_add_u32 s72, s72, 0x2000
	s_addc_u32 s73, s73, 0
	global_load_dwordx4 v[224:227], v140, s[72:73] sc0 sc1
	s_add_u32 s72, s72, 0x2000
	s_addc_u32 s73, s73, 0
	global_load_dwordx4 v[228:231], v140, s[72:73] sc0 sc1
	s_add_u32 s72, s72, 0x2000
	s_addc_u32 s73, s73, 0
	global_load_dwordx4 v[232:235], v140, s[72:73] sc0 sc1
	s_add_u32 s72, s72, 0x2000
	s_addc_u32 s73, s73, 0
	global_load_dwordx4 v[236:239], v140, s[72:73] sc0 sc1
	s_add_u32 s72, s72, 0x2000
	s_addc_u32 s73, s73, 0
	global_load_dwordx4 v[240:243], v140, s[72:73] sc0 sc1
	s_add_u32 s72, s72, 0x2000
	s_addc_u32 s73, s73, 0
	global_load_dwordx4 v[244:247], v140, s[72:73] sc0 sc1
	s_add_u32 s72, s72, 0x2000
	s_addc_u32 s73, s73, 0
	global_load_dwordx4 v[160:163], v140, s[72:73] sc0 sc1
	s_add_u32 s72, s72, 0x2000
	s_addc_u32 s73, s73, 0
	global_load_dwordx4 v[164:167], v140, s[72:73] sc0 sc1
	s_add_u32 s72, s72, 0x2000
	s_addc_u32 s73, s73, 0
	global_load_dwordx4 v[168:171], v140, s[72:73] sc0 sc1
	s_add_u32 s72, s72, 0x2000
	s_addc_u32 s73, s73, 0
	global_load_dwordx4 v[172:175], v140, s[72:73] sc0 sc1
	s_add_u32 s72, s72, 0x2000
	s_addc_u32 s73, s73, 0
	s_waitcnt vmcnt(15)
	v_pk_add_f32 v[64:65], v[64:65], v[200:201]
	v_pk_add_f32 v[66:67], v[66:67], v[202:203]
	s_waitcnt vmcnt(14)
	v_pk_add_f32 v[68:69], v[68:69], v[204:205]
	v_pk_add_f32 v[70:71], v[70:71], v[206:207]
	s_waitcnt vmcnt(13)
	v_pk_add_f32 v[72:73], v[72:73], v[208:209]
	v_pk_add_f32 v[74:75], v[74:75], v[210:211]
	s_waitcnt vmcnt(12)
	v_pk_add_f32 v[76:77], v[76:77], v[212:213]
	v_pk_add_f32 v[78:79], v[78:79], v[214:215]
	s_waitcnt vmcnt(11)
	v_pk_add_f32 v[80:81], v[80:81], v[216:217]
	v_pk_add_f32 v[82:83], v[82:83], v[218:219]
	s_waitcnt vmcnt(10)
	v_pk_add_f32 v[84:85], v[84:85], v[220:221]
	v_pk_add_f32 v[86:87], v[86:87], v[222:223]
	s_waitcnt vmcnt(9)
	v_pk_add_f32 v[88:89], v[88:89], v[224:225]
	v_pk_add_f32 v[90:91], v[90:91], v[226:227]
	s_waitcnt vmcnt(8)
	v_pk_add_f32 v[92:93], v[92:93], v[228:229]
	v_pk_add_f32 v[94:95], v[94:95], v[230:231]
	s_waitcnt vmcnt(7)
	v_pk_add_f32 v[96:97], v[96:97], v[232:233]
	v_pk_add_f32 v[98:99], v[98:99], v[234:235]
	s_waitcnt vmcnt(6)
	v_pk_add_f32 v[100:101], v[100:101], v[236:237]
	v_pk_add_f32 v[102:103], v[102:103], v[238:239]
	s_waitcnt vmcnt(5)
	v_pk_add_f32 v[104:105], v[104:105], v[240:241]
	v_pk_add_f32 v[106:107], v[106:107], v[242:243]
	s_waitcnt vmcnt(4)
	v_pk_add_f32 v[108:109], v[108:109], v[244:245]
	v_pk_add_f32 v[110:111], v[110:111], v[246:247]
	s_waitcnt vmcnt(3)
	v_pk_add_f32 v[112:113], v[112:113], v[160:161]
	v_pk_add_f32 v[114:115], v[114:115], v[162:163]
	s_waitcnt vmcnt(2)
	v_pk_add_f32 v[116:117], v[116:117], v[164:165]
	v_pk_add_f32 v[118:119], v[118:119], v[166:167]
	s_waitcnt vmcnt(1)
	v_pk_add_f32 v[120:121], v[120:121], v[168:169]
	v_pk_add_f32 v[122:123], v[122:123], v[170:171]
	s_waitcnt vmcnt(0)
	v_pk_add_f32 v[124:125], v[124:125], v[172:173]
	v_pk_add_f32 v[126:127], v[126:127], v[174:175]
.Lp5b_poll1:
	global_load_dword v142, v141, s[20:21] offset:3204 sc1
	s_waitcnt vmcnt(0)
	v_readfirstlane_b32 s69, v142
	s_nop 0
	s_cmp_ge_u32 s69, 8
	s_cbranch_scc1 .Lp5b_go1
	s_sleep 1
	s_branch .Lp5b_poll1
.Lp5b_go1:
	s_add_u32 s72, s70, 0x0
	s_addc_u32 s73, s71, 0
	global_load_dwordx4 v[200:203], v140, s[72:73] sc0 sc1
	s_add_u32 s72, s72, 0x2000
	s_addc_u32 s73, s73, 0
	global_load_dwordx4 v[204:207], v140, s[72:73] sc0 sc1
	s_add_u32 s72, s72, 0x2000
	s_addc_u32 s73, s73, 0
	global_load_dwordx4 v[208:211], v140, s[72:73] sc0 sc1
	s_add_u32 s72, s72, 0x2000
	s_addc_u32 s73, s73, 0
	global_load_dwordx4 v[212:215], v140, s[72:73] sc0 sc1
	s_add_u32 s72, s72, 0x2000
	s_addc_u32 s73, s73, 0
	global_load_dwordx4 v[216:219], v140, s[72:73] sc0 sc1
	s_add_u32 s72, s72, 0x2000
	s_addc_u32 s73, s73, 0
	global_load_dwordx4 v[220:223], v140, s[72:73] sc0 sc1
	s_add_u32 s72, s72, 0x2000
	s_addc_u32 s73, s73, 0
	global_load_dwordx4 v[224:227], v140, s[72:73] sc0 sc1
	s_add_u32 s72, s72, 0x2000
	s_addc_u32 s73, s73, 0
	global_load_dwordx4 v[228:231], v140, s[72:73] sc0 sc1
	s_add_u32 s72, s72, 0x2000
	s_addc_u32 s73, s73, 0
	global_load_dwordx4 v[232:235], v140, s[72:73] sc0 sc1
	s_add_u32 s72, s72, 0x2000
	s_addc_u32 s73, s73, 0
	global_load_dwordx4 v[236:239], v140, s[72:73] sc0 sc1
	s_add_u32 s72, s72, 0x2000
	s_addc_u32 s73, s73, 0
	global_load_dwordx4 v[240:243], v140, s[72:73] sc0 sc1
	s_add_u32 s72, s72, 0x2000
	s_addc_u32 s73, s73, 0
	global_load_dwordx4 v[244:247], v140, s[72:73] sc0 sc1
	s_add_u32 s72, s72, 0x2000
	s_addc_u32 s73, s73, 0
	global_load_dwordx4 v[160:163], v140, s[72:73] sc0 sc1
	s_add_u32 s72, s72, 0x2000
	s_addc_u32 s73, s73, 0
	global_load_dwordx4 v[164:167], v140, s[72:73] sc0 sc1
	s_add_u32 s72, s72, 0x2000
	s_addc_u32 s73, s73, 0
	global_load_dwordx4 v[168:171], v140, s[72:73] sc0 sc1
	s_add_u32 s72, s72, 0x2000
	s_addc_u32 s73, s73, 0
	global_load_dwordx4 v[172:175], v140, s[72:73] sc0 sc1
	s_add_u32 s72, s72, 0x2000
	s_addc_u32 s73, s73, 0
	s_waitcnt vmcnt(15)
; #define PG8_BAR __builtin_amdgcn_s_barrier()
; template <int KK, class Epi, class Sched, bool ALIGN_EPI = true>
; __device__ __forceinline__ void gemm_phase(LAS unsigned char* lds, const bf16* gA, const bf16* gBt, const Sched& S, const Epi& E, const int wid) {
;     ...
;         if constexpr (ALIGN_EPI) { if (wr == 0) PG8_BAR; }
;         E(acc, cur, wr, wc, fr, fq);
	v_pk_add_f32 v[0:1], v[0:1], v[200:201]
	v_pk_add_f32 v[2:3], v[2:3], v[202:203]
	s_waitcnt vmcnt(14)
	v_pk_add_f32 v[4:5], v[4:5], v[204:205]
	v_pk_add_f32 v[6:7], v[6:7], v[206:207]
	s_waitcnt vmcnt(13)
	v_pk_add_f32 v[8:9], v[8:9], v[208:209]
	v_pk_add_f32 v[10:11], v[10:11], v[210:211]
	s_waitcnt vmcnt(12)
	v_pk_add_f32 v[12:13], v[12:13], v[212:213]
	v_pk_add_f32 v[14:15], v[14:15], v[214:215]
	s_waitcnt vmcnt(11)
	v_pk_add_f32 v[16:17], v[16:17], v[216:217]
	v_pk_add_f32 v[18:19], v[18:19], v[218:219]
	s_waitcnt vmcnt(10)
	v_pk_add_f32 v[20:21], v[20:21], v[220:221]
	v_pk_add_f32 v[22:23], v[22:23], v[222:223]
	s_waitcnt vmcnt(9)
	v_pk_add_f32 v[24:25], v[24:25], v[224:225]
	v_pk_add_f32 v[26:27], v[26:27], v[226:227]
	s_waitcnt vmcnt(8)
	v_pk_add_f32 v[28:29], v[28:29], v[228:229]
	v_pk_add_f32 v[30:31], v[30:31], v[230:231]
	s_waitcnt vmcnt(7)
	v_pk_add_f32 v[32:33], v[32:33], v[232:233]
	v_pk_add_f32 v[34:35], v[34:35], v[234:235]
	s_waitcnt vmcnt(6)
	v_pk_add_f32 v[36:37], v[36:37], v[236:237]
	v_pk_add_f32 v[38:39], v[38:39], v[238:239]
	s_waitcnt vmcnt(5)
	v_pk_add_f32 v[40:41], v[40:41], v[240:241]
	v_pk_add_f32 v[42:43], v[42:43], v[242:243]
	s_waitcnt vmcnt(4)
	v_pk_add_f32 v[44:45], v[44:45], v[244:245]
	v_pk_add_f32 v[46:47], v[46:47], v[246:247]
	s_waitcnt vmcnt(3)
	v_pk_add_f32 v[48:49], v[48:49], v[160:161]
	v_pk_add_f32 v[50:51], v[50:51], v[162:163]
	s_waitcnt vmcnt(2)
	v_pk_add_f32 v[52:53], v[52:53], v[164:165]
	v_pk_add_f32 v[54:55], v[54:55], v[166:167]
	s_waitcnt vmcnt(1)
	v_pk_add_f32 v[56:57], v[56:57], v[168:169]
	v_pk_add_f32 v[58:59], v[58:59], v[170:171]
	s_waitcnt vmcnt(0)
	v_pk_add_f32 v[60:61], v[60:61], v[172:173]
	v_pk_add_f32 v[62:63], v[62:63], v[174:175]
	global_load_dwordx4 v[200:203], v140, s[72:73] sc0 sc1
	s_add_u32 s72, s72, 0x2000
	s_addc_u32 s73, s73, 0
	global_load_dwordx4 v[204:207], v140, s[72:73] sc0 sc1
	s_add_u32 s72, s72, 0x2000
	s_addc_u32 s73, s73, 0
	global_load_dwordx4 v[208:211], v140, s[72:73] sc0 sc1
	s_add_u32 s72, s72, 0x2000
	s_addc_u32 s73, s73, 0
	global_load_dwordx4 v[212:215], v140, s[72:73] sc0 sc1
	s_add_u32 s72, s72, 0x2000
	s_addc_u32 s73, s73, 0
	global_load_dwordx4 v[216:219], v140, s[72:73] sc0 sc1
	s_add_u32 s72, s72, 0x2000
	s_addc_u32 s73, s73, 0
	global_load_dwordx4 v[220:223], v140, s[72:73] sc0 sc1
	s_add_u32 s72, s72, 0x2000
	s_addc_u32 s73, s73, 0
	global_load_dwordx4 v[224:227], v140, s[72:73] sc0 sc1
	s_add_u32 s72, s72, 0x2000
	s_addc_u32 s73, s73, 0
	global_load_dwordx4 v[228:231], v140, s[72:73] sc0 sc1
	s_add_u32 s72, s72, 0x2000
	s_addc_u32 s73, s73, 0
	global_load_dwordx4 v[232:235], v140, s[72:73] sc0 sc1
	s_add_u32 s72, s72, 0x2000
	s_addc_u32 s73, s73, 0
	global_load_dwordx4 v[236:239], v140, s[72:73] sc0 sc1
	s_add_u32 s72, s72, 0x2000
	s_addc_u32 s73, s73, 0
	global_load_dwordx4 v[240:243], v140, s[72:73] sc0 sc1
	s_add_u32 s72, s72, 0x2000
	s_addc_u32 s73, s73, 0
	global_load_dwordx4 v[244:247], v140, s[72:73] sc0 sc1
	s_add_u32 s72, s72, 0x2000
	s_addc_u32 s73, s73, 0
	global_load_dwordx4 v[160:163], v140, s[72:73] sc0 sc1
	s_add_u32 s72, s72, 0x2000
	s_addc_u32 s73, s73, 0
	global_load_dwordx4 v[164:167], v140, s[72:73] sc0 sc1
	s_add_u32 s72, s72, 0x2000
	s_addc_u32 s73, s73, 0
	global_load_dwordx4 v[168:171], v140, s[72:73] sc0 sc1
	s_add_u32 s72, s72, 0x2000
	s_addc_u32 s73, s73, 0
	global_load_dwordx4 v[172:175], v140, s[72:73] sc0 sc1
	s_add_u32 s72, s72, 0x2000
	s_addc_u32 s73, s73, 0
	s_waitcnt vmcnt(15)
	v_pk_add_f32 v[64:65], v[64:65], v[200:201]
	v_pk_add_f32 v[66:67], v[66:67], v[202:203]
	s_waitcnt vmcnt(14)
	v_pk_add_f32 v[68:69], v[68:69], v[204:205]
	v_pk_add_f32 v[70:71], v[70:71], v[206:207]
	s_waitcnt vmcnt(13)
	v_pk_add_f32 v[72:73], v[72:73], v[208:209]
	v_pk_add_f32 v[74:75], v[74:75], v[210:211]
	s_waitcnt vmcnt(12)
	v_pk_add_f32 v[76:77], v[76:77], v[212:213]
	v_pk_add_f32 v[78:79], v[78:79], v[214:215]
	s_waitcnt vmcnt(11)
	v_pk_add_f32 v[80:81], v[80:81], v[216:217]
	v_pk_add_f32 v[82:83], v[82:83], v[218:219]
	s_waitcnt vmcnt(10)
	v_pk_add_f32 v[84:85], v[84:85], v[220:221]
	v_pk_add_f32 v[86:87], v[86:87], v[222:223]
	s_waitcnt vmcnt(9)
	v_pk_add_f32 v[88:89], v[88:89], v[224:225]
	v_pk_add_f32 v[90:91], v[90:91], v[226:227]
	s_waitcnt vmcnt(8)
	v_pk_add_f32 v[92:93], v[92:93], v[228:229]
	v_pk_add_f32 v[94:95], v[94:95], v[230:231]
	s_waitcnt vmcnt(7)
	v_pk_add_f32 v[96:97], v[96:97], v[232:233]
	v_pk_add_f32 v[98:99], v[98:99], v[234:235]
	s_waitcnt vmcnt(6)
	v_pk_add_f32 v[100:101], v[100:101], v[236:237]
	v_pk_add_f32 v[102:103], v[102:103], v[238:239]
	s_waitcnt vmcnt(5)
	v_pk_add_f32 v[104:105], v[104:105], v[240:241]
	v_pk_add_f32 v[106:107], v[106:107], v[242:243]
	s_waitcnt vmcnt(4)
	v_pk_add_f32 v[108:109], v[108:109], v[244:245]
	v_pk_add_f32 v[110:111], v[110:111], v[246:247]
	s_waitcnt vmcnt(3)
	v_pk_add_f32 v[112:113], v[112:113], v[160:161]
	v_pk_add_f32 v[114:115], v[114:115], v[162:163]
	s_waitcnt vmcnt(2)
	v_pk_add_f32 v[116:117], v[116:117], v[164:165]
	v_pk_add_f32 v[118:119], v[118:119], v[166:167]
	s_waitcnt vmcnt(1)
	v_pk_add_f32 v[120:121], v[120:121], v[168:169]
	v_pk_add_f32 v[122:123], v[122:123], v[170:171]
	s_waitcnt vmcnt(0)
	v_pk_add_f32 v[124:125], v[124:125], v[172:173]
	v_pk_add_f32 v[126:127], v[126:127], v[174:175]

;     __device__ __forceinline__ bool next(int i, Unit& u) const {
;         if (v < nskip) return false;
;         const int L = i * (G - nskip) + (v - nskip); if (L >= (33792 / BM) * NN) return false;
;         constexpr int NM = 33792 / BM, NFULL = (NM / 8) * 8 * NN;
;         if (L < NFULL) { const int g = L / (8 * NN), idx = L % (8 * NN); u.pm = g * 8 + (idx & 7); u.pn = idx >> 3; }
;         else { constexpr int GS = NM % 8 ? NM % 8 : 8; const int idx = L - NFULL; u.pm = (NM / 8) * 8 + idx % GS; u.pn = idx / GS; }
;         return true;
; template <int l>
; __device__ __forceinline__ void run_layer(LAS unsigned char* lds, unsigned char* ws_in, float* out_in, const float* x_p, const float* x_s, const PIn* pin, const int G, const int bid, const int wave) {
;     ...
;             pg8::RowOrderSkip<DM / 256> S2; S2.init(G, bid, (G > 16) ? (MT / 256 * 4) % G : 0);
;             EpiPP E2{ws, out};
;             pg8::gemm_phase<DPLE, EpiPP, pg8::RowOrderSkip<DM / 256>>(lds, (const bf16*)(ws + WS_PB) + (size_t)l * MT * DPLE, (const bf16*)(wb + W_PP), S2, E2, wave);
.LBB0_1304:
	s_cmp_eq_u32 s64, 0x100
	s_cselect_b32 s12, 64, s12
	v_mov_b32_e32 v0, v196
	s_cmp_lt_i32 s0, s12
	s_cbranch_scc1 .LBB0_1331
	s_sub_i32 s0, s0, s12
	s_cmpk_gt_i32 s0, 0x20f
	s_cbranch_scc1 .LBB0_1331
	s_cmpk_gt_i32 s0, 0x1ff
	s_cbranch_scc0 .LBB0_1311
	s_add_i32 s1, s0, 0xfffffe00
	s_and_b32 s2, s0, 3
	s_or_b32 s30, s2, 0x80
	s_lshr_b32 s26, s1, 2
	s_cbranch_execz .LBB0_1312
	s_branch .LBB0_1313
